# mla_sample_unit PV (value blocks 1..3): three V fragment reads kept in flight with counted lgkmcnt instead of read-wait-MFMA one at a time
# baseline (speedup 1.0000x reference)
; #define LAS __attribute__((address_space(3)))
; #define MFMA32(a, b, c) __builtin_amdgcn_mfma_f32_32x32x16_bf16((a), (b), (c), 0, 0, 0)
; __device__ __forceinline__ void mla_sample_unit(LAS unsigned char* lds, size_t ws_q, size_t ws_olat, size_t ws_mixed, int b) {
;     ...
;             float ls = 0.f;
; #pragma unroll
;             for (int r = 0; r < 16; ++r) { s0[r] = __builtin_amdgcn_exp2f(s0[r]); s1[r] = __builtin_amdgcn_exp2f(s1[r]); ls += s0[r] + s1[r]; }
;             lrun += ls;
;             bf16x8 pf[4]; pf[0] = pack8(s0, 0); pf[1] = pack8(s0, 8); pf[2] = pack8(s1, 0); pf[3] = pack8(s1, 8);
;             const LAS unsigned char* vb = lds + KV0 + 2 * KB + buf * VB + (r32 * VP + 4 * hi) * 2;
; #pragma unroll
;             for (int dp = 0; dp < NDB; ++dp) {
;                 u32x2 vl[4], vh[4];
; #pragma unroll
;                 for (int q = 0; q < 4; ++q) { const LAS unsigned char* vp = vb + (dp * 32 * VP + 16 * q) * 2; vl[q] = *(const LAS u32x2*)vp; vh[q] = *(const LAS u32x2*)(vp + 16); }
; #pragma unroll
;                 for (int q = 0; q < 4; ++q) { const u32x4 v4 = (u32x4){vl[q].x, vl[q].y, vh[q].x, vh[q].y}; o[dp] = MFMA32(__builtin_bit_cast(bf16x8, v4), pf[q], o[dp]); }
;             }
.LBB0_900:
	v_exp_f32_e32 v1, v80
	v_exp_f32_e32 v110, v96
	v_exp_f32_e32 v94, v81
	v_exp_f32_e32 v80, v97
	v_mov_b32_e32 v95, v0
	v_add_f32_e32 v81, v110, v1
	v_exp_f32_e32 v111, v98
	v_pk_add_f32 v[92:93], v[80:81], v[94:95]
	v_exp_f32_e32 v81, v82
	v_pk_add_f32 v[96:97], v[92:93], v[92:93] op_sel_hi:[0,1]
	v_exp_f32_e32 v96, v83
	v_exp_f32_e32 v82, v99
	v_add_f32_e32 v83, v111, v81
	v_exp_f32_e32 v186, v100
	v_exp_f32_e32 v108, v3
	v_pk_add_f32 v[92:93], v[82:83], v[96:97]
	v_exp_f32_e32 v83, v84
	v_pk_add_f32 v[98:99], v[92:93], v[92:93] op_sel_hi:[0,1]
	v_exp_f32_e32 v98, v85
	v_exp_f32_e32 v84, v101
	v_add_f32_e32 v85, v186, v83
	v_cvt_pk_bf16_f32 v3, v81, v96
	v_cvt_pk_bf16_f32 v80, v110, v80
	v_pk_add_f32 v[92:93], v[84:85], v[98:99]
	v_exp_f32_e32 v85, v86
	v_pk_add_f32 v[100:101], v[92:93], v[92:93] op_sel_hi:[0,1]
	v_exp_f32_e32 v99, v102
	v_exp_f32_e32 v100, v87
	v_exp_f32_e32 v86, v103
	v_cvt_pk_bf16_f32 v81, v111, v82
	v_add_f32_e32 v87, v99, v85
	v_cvt_pk_bf16_f32 v82, v186, v84
	v_pk_add_f32 v[92:93], v[86:87], v[100:101]
	v_exp_f32_e32 v87, v88
	v_pk_add_f32 v[102:103], v[92:93], v[92:93] op_sel_hi:[0,1]
	v_exp_f32_e32 v101, v14
	v_exp_f32_e32 v102, v89
	v_exp_f32_e32 v14, v15
	v_add_f32_e32 v15, v101, v87
	v_pk_add_f32 v[88:89], v[14:15], v[102:103]
	s_nop 0
	v_pk_add_f32 v[104:105], v[88:89], v[88:89] op_sel_hi:[0,1]
	v_exp_f32_e32 v15, v90
	v_exp_f32_e32 v103, v4
	v_exp_f32_e32 v104, v91
	v_exp_f32_e32 v88, v5
	ds_read2_b64 v[90:93], v183 offset1:2
	v_add_f32_e32 v89, v103, v15
	v_pk_add_f32 v[4:5], v[88:89], v[104:105]
	s_nop 0
	v_pk_add_f32 v[106:107], v[4:5], v[4:5] op_sel_hi:[0,1]
	v_exp_f32_e32 v89, v12
	v_exp_f32_e32 v105, v2
	v_exp_f32_e32 v106, v13
	v_cvt_pk_bf16_f32 v2, v1, v94
	v_cvt_pk_bf16_f32 v4, v83, v98
	v_cvt_pk_bf16_f32 v5, v85, v100
	ds_read2_b64 v[94:97], v183 offset0:4 offset1:6
	v_add_f32_e32 v109, v105, v89
	s_waitcnt lgkmcnt(0)
	v_mfma_f32_32x32x16_bf16 v[64:79], v[90:93], v[2:5], v[64:79]
	v_add_f32_e64 v12, v108, v106
	v_add_f32_e64 v13, v109, v107
	v_exp_f32_e32 v1, v10
	v_pk_add_f32 v[12:13], v[12:13], v[12:13] op_sel_hi:[0,1]
	v_exp_f32_e32 v12, v11
	v_cvt_pk_bf16_f32 v90, v87, v102
	v_cvt_pk_bf16_f32 v91, v15, v104
	v_cvt_pk_bf16_f32 v92, v89, v106
	v_cvt_pk_bf16_f32 v93, v1, v12
	v_cvt_pk_bf16_f32 v83, v99, v86
	ds_read2_b64 v[84:87], v183 offset0:12 offset1:14
	v_mfma_f32_32x32x16_bf16 v[64:79], v[94:97], v[90:93], v[64:79]
	ds_read2_b64 v[94:97], v183 offset0:8 offset1:10
	v_exp_f32_e32 v15, v8
	v_cvt_pk_bf16_f32 v8, v101, v14
	v_cvt_pk_bf16_f32 v10, v105, v108
	v_add_u32_e32 v14, 0x1000, v183
	s_waitcnt lgkmcnt(0)
	v_mfma_f32_32x32x16_bf16 v[64:79], v[94:97], v[80:83], v[64:79]
	v_exp_f32_e32 v94, v9
	v_cvt_pk_bf16_f32 v9, v103, v88
	v_add_f32_e32 v95, v15, v1
	v_cvt_pk_bf16_f32 v11, v15, v94
	v_pk_add_f32 v[12:13], v[94:95], v[12:13]
	s_nop 0
	v_mfma_f32_32x32x16_bf16 v[64:79], v[84:87], v[8:11], v[64:79]
	v_add_u32_e32 v252, 0x2000, v183
	v_add_u32_e32 v253, 0x3000, v183
	ds_read2_b64 v[84:87], v14 offset0:32 offset1:34
	ds_read2_b64 v[94:97], v14 offset0:36 offset1:38
	ds_read2_b64 v[248:251], v14 offset0:40 offset1:42
	v_add_f32_e32 v1, v12, v13
	v_add_f32_e32 v7, v7, v1
	s_waitcnt lgkmcnt(2)
	v_mfma_f32_32x32x16_bf16 v[48:63], v[84:87], v[2:5], v[48:63]
	ds_read2_b64 v[84:87], v14 offset0:44 offset1:46
	s_waitcnt lgkmcnt(2)
	v_mfma_f32_32x32x16_bf16 v[48:63], v[94:97], v[90:93], v[48:63]
	ds_read2_b64 v[94:97], v252 offset0:64 offset1:66
	s_waitcnt lgkmcnt(2)
	v_mfma_f32_32x32x16_bf16 v[48:63], v[248:251], v[80:83], v[48:63]
	ds_read2_b64 v[248:251], v252 offset0:68 offset1:70
	s_waitcnt lgkmcnt(2)
	v_mfma_f32_32x32x16_bf16 v[48:63], v[84:87], v[8:11], v[48:63]
	ds_read2_b64 v[84:87], v252 offset0:72 offset1:74
	s_waitcnt lgkmcnt(2)
	v_mfma_f32_32x32x16_bf16 v[32:47], v[94:97], v[2:5], v[32:47]
	ds_read2_b64 v[94:97], v252 offset0:76 offset1:78
	s_waitcnt lgkmcnt(2)
	v_mfma_f32_32x32x16_bf16 v[32:47], v[248:251], v[90:93], v[32:47]
	ds_read2_b64 v[248:251], v253 offset0:96 offset1:98
	s_waitcnt lgkmcnt(2)
	v_mfma_f32_32x32x16_bf16 v[32:47], v[84:87], v[80:83], v[32:47]
	ds_read2_b64 v[84:87], v253 offset0:100 offset1:102
	s_waitcnt lgkmcnt(2)
	v_mfma_f32_32x32x16_bf16 v[32:47], v[94:97], v[8:11], v[32:47]
	ds_read2_b64 v[94:97], v253 offset0:104 offset1:106
	s_waitcnt lgkmcnt(2)
	v_mfma_f32_32x32x16_bf16 v[16:31], v[248:251], v[2:5], v[16:31]
	ds_read2_b64 v[248:251], v253 offset0:108 offset1:110
	s_waitcnt lgkmcnt(2)
	v_mfma_f32_32x32x16_bf16 v[16:31], v[84:87], v[90:93], v[16:31]
	s_waitcnt lgkmcnt(1)
	v_mfma_f32_32x32x16_bf16 v[16:31], v[94:97], v[80:83], v[16:31]
	s_waitcnt lgkmcnt(0)
	v_mfma_f32_32x32x16_bf16 v[16:31], v[248:251], v[8:11], v[16:31]
